# v26 + H0 K fragments 5/6 renamed to v[242:249] so H0 staging loads also issue at the segment head; bit-identical
# baseline (speedup 1.0000x reference)
; template <int KB, bool HASY>
; __device__ __forceinline__ void phaseA(f32x16& X0, f32x16& X1, f32x16& Y0, f32x16& Y1, bf16x8& pa0, bf16x8& pa1, bf16x8& pa2, bf16x8& pa3,
;                                        const bf16x8* qr, const f32x16& negm, int kaddr, VFr& vf, int vb, float& l_reg) {
;   SBAR();
;   float ls = 0.f;
;   bf16x8 k0 = rd128<KOFF(KB, 0, 0)>(kaddr), k1 = rd128<KOFF(KB, 1, 0)>(kaddr), k2 = rd128<KOFF(KB, 0, 1)>(kaddr), k3 = rd128<KOFF(KB, 1, 1)>(kaddr);
;   if (HASY) { EXP4(Y0, 0); EXP4(Y0, 4); }
;   SBAR(); WAIT4(k0, k1, k2, k3);
;   bf16x8 k4 = rd128<KOFF(KB, 0, 2)>(kaddr), k5 = rd128<KOFF(KB, 1, 2)>(kaddr), k6 = rd128<KOFF(KB, 0, 3)>(kaddr), k7 = rd128<KOFF(KB, 1, 3)>(kaddr);
;   SBAR();
;   X0 = MF(k0, qr[0], negm); if (HASY) { EXP4(Y0, 8); SUM4(Y0, 0); } SBAR();
;   X1 = MF(k1, qr[0], negm); if (HASY) { EXP4(Y0, 12); SUM4(Y0, 4); } SBAR();
;   X0 = MF(k2, qr[1], X0); if (HASY) { PACK8(Y0, 0, pa0); } SBAR();
;   X1 = MF(k3, qr[1], X1); if (HASY) { EXP4(Y1, 0); SUM4(Y0, 8); } SBAR();
;   WAIT4(k4, k5, k6, k7);
;   bf16x8 k8 = rd128<KOFF(KB, 0, 4)>(kaddr), k9 = rd128<KOFF(KB, 1, 4)>(kaddr), k10 = rd128<KOFF(KB, 0, 5)>(kaddr), k11 = rd128<KOFF(KB, 1, 5)>(kaddr);
;   SBAR();
;   X0 = MF(k4, qr[2], X0); if (HASY) { EXP4(Y1, 4); SUM4(Y0, 12); } SBAR();
;   X1 = MF(k5, qr[2], X1); if (HASY) { PACK8(Y0, 8, pa1); } SBAR();
;   X0 = MF(k6, qr[3], X0); if (HASY) { EXP4(Y1, 8); SUM4(Y1, 0); } SBAR();
;   X1 = MF(k7, qr[3], X1); if (HASY) { EXP4(Y1, 12); SUM4(Y1, 4); } SBAR();
;   WAIT4(k8, k9, k10, k11);
;   SBAR();
;   X0 = MF(k8, qr[4], X0); if (HASY) { PACK8(Y1, 0, pa2); } SBAR();
;   X1 = MF(k9, qr[4], X1); if (HASY) { SUM4(Y1, 8); SUM4(Y1, 12); } SBAR();
;   X0 = MF(k10, qr[5], X0); if (HASY) { PACK8(Y1, 8, pa3); } SBAR();
;   X1 = MF(k11, qr[5], X1); if (HASY) vfr_issue<0>(vf, vb);
;   l_reg += ls;
;   SBAR();
; }
; template <bool HASX>
; __device__ __forceinline__ float phaseB(f32x16* o, bf16x8 pa0, bf16x8 pa1, bf16x8 pa2, bf16x8 pa3, VFr& f, int vb, const f32x16& X0, const f32x16& X1) {
;   SBAR(); VWAIT(f); VFr g; vfr_issue<2>(g, vb); SBAR();
;   float a = 0.f, b = 0.f;
;   o[0] = MF(pa0, PKV(f.a0, f.b0), o[0]); SBAR(); o[1] = MF(pa0, PKV(f.c0, f.d0), o[1]);
;   if (HASX) { a = MX3(X0[0], X0[1], X1[0]); b = MX3(X0[2], X0[3], X1[1]); a = MX3(a, X1[2], X1[3]); b = MX3(b, X0[4], X0[5]); } SBAR();
.LBB0_249:
	s_barrier
	ds_read_b128 v[34:37], v184 offset:0x3400
	ds_read_b128 v[38:41], v184 offset:0x4e00
	ds_read_b128 v[42:45], v184 offset:0x3420
	ds_read_b128 v[46:49], v184 offset:0x4e20
	ds_read_b128 v[242:245], v184 offset:0x3440
	ds_read_b128 v[246:249], v184 offset:0x4e40
	ds_read_b128 v[204:207], v184 offset:0x3460
	ds_read_b128 v[208:211], v184 offset:0x4e60
	s_add_i32 s18, s52, 0xffffe000
	buffer_load_dwordx4 v[170:173], v185, s[64:67], s18 offen
	buffer_load_dwordx4 v[174:177], v185, s[44:47], s18 offen
	s_add_i32 s28, s68, 0xfffff000
	buffer_load_dwordx4 v[158:161], v186, s[60:63], s28 offen
	s_waitcnt lgkmcnt(7)
	v_mfma_f32_32x32x16_bf16 v[114:129], v[34:37], v[150:153], v[50:65]
	v_exp_f32_e32 v88, v90
	v_exp_f32_e32 v89, v91
	v_exp_f32_e32 v90, v92
	v_exp_f32_e32 v91, v93
	s_waitcnt lgkmcnt(6)
	v_mfma_f32_32x32x16_bf16 v[98:113], v[38:41], v[150:153], v[50:65]
	v_exp_f32_e32 v92, v94
	v_exp_f32_e32 v93, v95
	v_exp_f32_e32 v94, v96
	v_exp_f32_e32 v95, v97
	s_waitcnt lgkmcnt(5)
	v_mfma_f32_32x32x16_bf16 v[114:129], v[42:45], v[146:149], v[114:129]
	v_cvt_pk_bf16_f32 v34, v82, v195
	v_cvt_pk_bf16_f32 v35, v84, v196
	v_cvt_pk_bf16_f32 v36, v83, v85
	v_cvt_pk_bf16_f32 v37, v86, v87
	s_waitcnt lgkmcnt(4)
	v_mfma_f32_32x32x16_bf16 v[98:113], v[46:49], v[146:149], v[98:113]
	v_exp_f32_e32 v96, v66
	v_exp_f32_e32 v97, v67
	v_exp_f32_e32 v197, v68
	v_exp_f32_e32 v198, v69
	ds_read_b128 v[38:41], v184 offset:0x3480
	ds_read_b128 v[66:69], v184 offset:0x4e80
	ds_read_b128 v[212:215], v184 offset:0x34a0
	ds_read_b128 v[216:219], v184 offset:0x4ea0
	s_waitcnt lgkmcnt(4)
	v_mfma_f32_32x32x16_bf16 v[114:129], v[242:245], v[142:145], v[114:129]
	v_exp_f32_e32 v199, v70
	v_exp_f32_e32 v200, v71
	v_exp_f32_e32 v201, v72
	v_exp_f32_e32 v202, v73
	v_mfma_f32_32x32x16_bf16 v[98:113], v[246:249], v[142:145], v[98:113]
	v_cvt_pk_bf16_f32 v42, v88, v89
	v_cvt_pk_bf16_f32 v43, v90, v91
	v_cvt_pk_bf16_f32 v44, v92, v93
	v_cvt_pk_bf16_f32 v45, v94, v95
	v_mfma_f32_32x32x16_bf16 v[114:129], v[204:207], v[138:141], v[114:129]
	v_exp_f32_e32 v203, v74
	v_exp_f32_e32 v204, v75
	v_exp_f32_e32 v205, v76
	v_exp_f32_e32 v206, v77
	v_mfma_f32_32x32x16_bf16 v[98:113], v[208:211], v[138:141], v[98:113]
	v_exp_f32_e32 v207, v78
	v_exp_f32_e32 v208, v79
	v_exp_f32_e32 v209, v80
	v_exp_f32_e32 v210, v81
	s_waitcnt lgkmcnt(0)
	s_nop 0
	v_mfma_f32_32x32x16_bf16 v[114:129], v[38:41], v[134:137], v[114:129]
	v_cvt_pk_bf16_f32 v46, v96, v97
	v_cvt_pk_bf16_f32 v47, v197, v198
	v_cvt_pk_bf16_f32 v48, v199, v200
	v_cvt_pk_bf16_f32 v49, v201, v202
	v_mfma_f32_32x32x16_bf16 v[98:113], v[66:69], v[134:137], v[98:113]
	v_mfma_f32_32x32x16_bf16 v[114:129], v[212:215], v[130:133], v[114:129]
	v_cvt_pk_bf16_f32 v38, v203, v204
	v_cvt_pk_bf16_f32 v39, v205, v206
	v_cvt_pk_bf16_f32 v40, v207, v208
	v_cvt_pk_bf16_f32 v41, v209, v210
	ds_read_b64_tr_b16 v[78:79], v0 offset:0
	ds_read_b64_tr_b16 v[80:81], v0 offset:0x400
	ds_read_b64_tr_b16 v[74:75], v0 offset:0x200
	v_mfma_f32_32x32x16_bf16 v[98:113], v[216:219], v[130:133], v[98:113]
	ds_read_b64_tr_b16 v[76:77], v0 offset:0x600
	ds_read_b64_tr_b16 v[70:71], v0 offset:0x800
	ds_read_b64_tr_b16 v[72:73], v0 offset:0xc00
	ds_read_b64_tr_b16 v[66:67], v0 offset:0xa00
	ds_read_b64_tr_b16 v[68:69], v0 offset:0xe00
	s_waitcnt lgkmcnt(0)
	ds_read_b64_tr_b16 v[212:213], v0 offset:0x1000
	ds_read_b64_tr_b16 v[214:215], v0 offset:0x1400
	ds_read_b64_tr_b16 v[216:217], v0 offset:0x1200
	ds_read_b64_tr_b16 v[218:219], v0 offset:0x1600
	ds_read_b64_tr_b16 v[220:221], v0 offset:0x1800
	ds_read_b64_tr_b16 v[222:223], v0 offset:0x1c00
	ds_read_b64_tr_b16 v[228:229], v0 offset:0x1a00
	ds_read_b64_tr_b16 v[230:231], v0 offset:0x1e00
	v_mfma_f32_32x32x16_bf16 v[18:33], v[34:37], v[78:81], v[18:33]
	v_add_f32_e32 v238, v82, v195
	v_add_f32_e32 v239, v84, v196
	v_add_f32_e32 v240, v83, v85
	v_add_f32_e32 v241, v86, v87
	v_add_f32_e32 v238, v238, v239
	v_add_f32_e32 v240, v240, v241
	v_mfma_f32_32x32x16_bf16 v[2:17], v[34:37], v[74:77], v[2:17]
	v_max_f32_e32 v34, v114, v115
	v_max3_f32 v35, v116, v117, v99
	v_max3_f32 v34, v34, v98, v100
	v_max3_f32 v35, v35, v118, v119
	v_mfma_f32_32x32x16_bf16 v[18:33], v[42:45], v[70:73], v[18:33]
	v_max3_f32 v34, v34, v101, v120
	v_max3_f32 v35, v35, v102, v103
	v_add_f32_e32 v238, v240, v238
	v_add_f32_e32 v239, v88, v89
	v_add_f32_e32 v241, v90, v91
	v_mfma_f32_32x32x16_bf16 v[2:17], v[42:45], v[66:69], v[2:17]
	v_max3_f32 v34, v34, v121, v104
	v_max3_f32 v34, v34, v105, v124
	v_max3_f32 v35, v35, v122, v123
	v_add_f32_e32 v239, v239, v241
	v_add_f32_e32 v240, v92, v93
	v_add_f32_e32 v241, v94, v95
	s_waitcnt lgkmcnt(0)
	v_mfma_f32_32x32x16_bf16 v[18:33], v[46:49], v[212:215], v[18:33]
	v_max3_f32 v34, v34, v125, v108
	v_max3_f32 v35, v35, v106, v107
	v_add_f32_e32 v238, v239, v238
	v_add_f32_e32 v240, v240, v241
	s_waitcnt vmcnt(3)
	v_add_u32_e32 v67, s69, v187
	ds_write_b128 v67, v[162:165]
	v_mfma_f32_32x32x16_bf16 v[2:17], v[46:49], v[216:219], v[2:17]
	v_max3_f32 v34, v34, v109, v128
	v_max3_f32 v35, v35, v126, v127
	v_add_f32_e32 v238, v240, v238
	v_add_f32_e32 v239, v96, v97
	v_add_f32_e32 v241, v197, v198
	s_waitcnt vmcnt(2)
	ds_write_b128 v188, v[166:169] offset:24576
	v_mfma_f32_32x32x16_bf16 v[18:33], v[38:41], v[220:223], v[18:33]
	v_max3_f32 v34, v34, v129, v112
	v_max3_f32 v35, v35, v110, v111
	v_add_f32_e32 v239, v239, v241
	v_add_f32_e32 v240, v199, v200
	v_add_f32_e32 v241, v201, v202
	ds_write_b128 v193, v[154:157] offset:24704
	v_add_f32_e32 v238, v239, v238
	v_add_f32_e32 v240, v240, v241
	v_mfma_f32_32x32x16_bf16 v[2:17], v[38:41], v[228:231], v[2:17]
	v_max3_f32 v34, v34, v113, v35
	v_cmp_lt_f32_e32 vcc, s35, v34
	v_add_f32_e32 v238, v240, v238
	v_add_f32_e32 v239, v203, v204
	v_add_f32_e32 v241, v205, v206
	v_add_f32_e32 v239, v239, v241
	v_add_f32_e32 v240, v207, v208
	v_add_f32_e32 v241, v209, v210
	v_add_f32_e32 v238, v239, v238
	v_add_f32_e32 v240, v240, v241
	v_add_f32_e32 v238, v240, v238
	v_add_f32_e32 v194, v194, v238
	s_cbranch_vccnz .LBB0_272

; template <int KB, bool HASY>
; __device__ __forceinline__ void phaseA(f32x16& X0, f32x16& X1, f32x16& Y0, f32x16& Y1, bf16x8& pa0, bf16x8& pa1, bf16x8& pa2, bf16x8& pa3,
;                                        const bf16x8* qr, const f32x16& negm, int kaddr, VFr& vf, int vb, float& l_reg) {
;   SBAR();
;   float ls = 0.f;
;   bf16x8 k0 = rd128<KOFF(KB, 0, 0)>(kaddr), k1 = rd128<KOFF(KB, 1, 0)>(kaddr), k2 = rd128<KOFF(KB, 0, 1)>(kaddr), k3 = rd128<KOFF(KB, 1, 1)>(kaddr);
;   if (HASY) { EXP4(Y0, 0); EXP4(Y0, 4); }
;   SBAR(); WAIT4(k0, k1, k2, k3);
;   bf16x8 k4 = rd128<KOFF(KB, 0, 2)>(kaddr), k5 = rd128<KOFF(KB, 1, 2)>(kaddr), k6 = rd128<KOFF(KB, 0, 3)>(kaddr), k7 = rd128<KOFF(KB, 1, 3)>(kaddr);
;   SBAR();
;   X0 = MF(k0, qr[0], negm); if (HASY) { EXP4(Y0, 8); SUM4(Y0, 0); } SBAR();
;   X1 = MF(k1, qr[0], negm); if (HASY) { EXP4(Y0, 12); SUM4(Y0, 4); } SBAR();
;   X0 = MF(k2, qr[1], X0); if (HASY) { PACK8(Y0, 0, pa0); } SBAR();
;   X1 = MF(k3, qr[1], X1); if (HASY) { EXP4(Y1, 0); SUM4(Y0, 8); } SBAR();
;   WAIT4(k4, k5, k6, k7);
;   bf16x8 k8 = rd128<KOFF(KB, 0, 4)>(kaddr), k9 = rd128<KOFF(KB, 1, 4)>(kaddr), k10 = rd128<KOFF(KB, 0, 5)>(kaddr), k11 = rd128<KOFF(KB, 1, 5)>(kaddr);
;   SBAR();
;   X0 = MF(k4, qr[2], X0); if (HASY) { EXP4(Y1, 4); SUM4(Y0, 12); } SBAR();
;   X1 = MF(k5, qr[2], X1); if (HASY) { PACK8(Y0, 8, pa1); } SBAR();
;   X0 = MF(k6, qr[3], X0); if (HASY) { EXP4(Y1, 8); SUM4(Y1, 0); } SBAR();
;   X1 = MF(k7, qr[3], X1); if (HASY) { EXP4(Y1, 12); SUM4(Y1, 4); } SBAR();
;   WAIT4(k8, k9, k10, k11);
;   SBAR();
;   X0 = MF(k8, qr[4], X0); if (HASY) { PACK8(Y1, 0, pa2); } SBAR();
;   X1 = MF(k9, qr[4], X1); if (HASY) { SUM4(Y1, 8); SUM4(Y1, 12); } SBAR();
;   X0 = MF(k10, qr[5], X0); if (HASY) { PACK8(Y1, 8, pa3); } SBAR();
;   X1 = MF(k11, qr[5], X1); if (HASY) vfr_issue<0>(vf, vb);
;   l_reg += ls;
;   SBAR();
; }
; template <bool HASX>
; __device__ __forceinline__ float phaseB(f32x16* o, bf16x8 pa0, bf16x8 pa1, bf16x8 pa2, bf16x8 pa3, VFr& f, int vb, const f32x16& X0, const f32x16& X1) {
;   SBAR(); VWAIT(f); VFr g; vfr_issue<2>(g, vb); SBAR();
;   float a = 0.f, b = 0.f;
;   o[0] = MF(pa0, PKV(f.a0, f.b0), o[0]); SBAR(); o[1] = MF(pa0, PKV(f.c0, f.d0), o[1]);
;   if (HASX) { a = MX3(X0[0], X0[1], X1[0]); b = MX3(X0[2], X0[3], X1[1]); a = MX3(a, X1[2], X1[3]); b = MX3(b, X0[4], X0[5]); } SBAR();
.Lmy_y249:
	s_barrier
	ds_read_b128 v[34:37], v184 offset:0x3400
	ds_read_b128 v[38:41], v184 offset:0x4e00
	ds_read_b128 v[42:45], v184 offset:0x3420
	ds_read_b128 v[46:49], v184 offset:0x4e20
	ds_read_b128 v[242:245], v184 offset:0x3440
	ds_read_b128 v[246:249], v184 offset:0x4e40
	ds_read_b128 v[204:207], v184 offset:0x3460
	ds_read_b128 v[208:211], v184 offset:0x4e60
	s_add_i32 s18, s52, 0xffffe000
	buffer_load_dwordx4 v[170:173], v185, s[64:67], s18 offen
	buffer_load_dwordx4 v[174:177], v185, s[44:47], s18 offen
	s_waitcnt lgkmcnt(7)
	v_mfma_f32_32x32x16_bf16 v[114:129], v[34:37], v[150:153], v[50:65]
	v_exp_f32_e32 v88, v90
	v_exp_f32_e32 v89, v91
	v_exp_f32_e32 v90, v92
	v_exp_f32_e32 v91, v93
	s_waitcnt lgkmcnt(6)
	v_mfma_f32_32x32x16_bf16 v[98:113], v[38:41], v[150:153], v[50:65]
	v_exp_f32_e32 v92, v94
	v_exp_f32_e32 v93, v95
	v_exp_f32_e32 v94, v96
	v_exp_f32_e32 v95, v97
	s_waitcnt lgkmcnt(5)
	v_mfma_f32_32x32x16_bf16 v[114:129], v[42:45], v[146:149], v[114:129]
	v_cvt_pk_bf16_f32 v34, v82, v195
	v_cvt_pk_bf16_f32 v35, v84, v196
	v_cvt_pk_bf16_f32 v36, v83, v85
	v_cvt_pk_bf16_f32 v37, v86, v87
	s_waitcnt lgkmcnt(4)
	v_mfma_f32_32x32x16_bf16 v[98:113], v[46:49], v[146:149], v[98:113]
	v_exp_f32_e32 v96, v66
	v_exp_f32_e32 v97, v67
	v_exp_f32_e32 v197, v68
	v_exp_f32_e32 v198, v69
	ds_read_b128 v[38:41], v184 offset:0x3480
	ds_read_b128 v[66:69], v184 offset:0x4e80
	ds_read_b128 v[212:215], v184 offset:0x34a0
	ds_read_b128 v[216:219], v184 offset:0x4ea0
	s_waitcnt lgkmcnt(4)
	v_mfma_f32_32x32x16_bf16 v[114:129], v[242:245], v[142:145], v[114:129]
	v_exp_f32_e32 v199, v70
	v_exp_f32_e32 v200, v71
	v_exp_f32_e32 v201, v72
	v_exp_f32_e32 v202, v73
	v_mfma_f32_32x32x16_bf16 v[98:113], v[246:249], v[142:145], v[98:113]
	v_cvt_pk_bf16_f32 v42, v88, v89
	v_cvt_pk_bf16_f32 v43, v90, v91
	v_cvt_pk_bf16_f32 v44, v92, v93
	v_cvt_pk_bf16_f32 v45, v94, v95
	v_mfma_f32_32x32x16_bf16 v[114:129], v[204:207], v[138:141], v[114:129]
	v_exp_f32_e32 v203, v74
	v_exp_f32_e32 v204, v75
	v_exp_f32_e32 v205, v76
	v_exp_f32_e32 v206, v77
	v_mfma_f32_32x32x16_bf16 v[98:113], v[208:211], v[138:141], v[98:113]
	v_exp_f32_e32 v207, v78
	v_exp_f32_e32 v208, v79
	v_exp_f32_e32 v209, v80
	v_exp_f32_e32 v210, v81
	s_waitcnt lgkmcnt(0)
	s_nop 0
	v_mfma_f32_32x32x16_bf16 v[114:129], v[38:41], v[134:137], v[114:129]
	v_cvt_pk_bf16_f32 v46, v96, v97
	v_cvt_pk_bf16_f32 v47, v197, v198
	v_cvt_pk_bf16_f32 v48, v199, v200
	v_cvt_pk_bf16_f32 v49, v201, v202
	v_mfma_f32_32x32x16_bf16 v[98:113], v[66:69], v[134:137], v[98:113]
	v_mfma_f32_32x32x16_bf16 v[114:129], v[212:215], v[130:133], v[114:129]
	v_cvt_pk_bf16_f32 v38, v203, v204
	v_cvt_pk_bf16_f32 v39, v205, v206
	v_cvt_pk_bf16_f32 v40, v207, v208
	v_cvt_pk_bf16_f32 v41, v209, v210
	ds_read_b64_tr_b16 v[78:79], v0 offset:0
	ds_read_b64_tr_b16 v[80:81], v0 offset:0x400
	ds_read_b64_tr_b16 v[74:75], v0 offset:0x200
	v_mfma_f32_32x32x16_bf16 v[98:113], v[216:219], v[130:133], v[98:113]
	ds_read_b64_tr_b16 v[76:77], v0 offset:0x600
	ds_read_b64_tr_b16 v[70:71], v0 offset:0x800
	ds_read_b64_tr_b16 v[72:73], v0 offset:0xc00
	ds_read_b64_tr_b16 v[66:67], v0 offset:0xa00
	ds_read_b64_tr_b16 v[68:69], v0 offset:0xe00
	s_waitcnt lgkmcnt(0)
	ds_read_b64_tr_b16 v[212:213], v0 offset:0x1000
	ds_read_b64_tr_b16 v[214:215], v0 offset:0x1400
	ds_read_b64_tr_b16 v[216:217], v0 offset:0x1200
	ds_read_b64_tr_b16 v[218:219], v0 offset:0x1600
	ds_read_b64_tr_b16 v[220:221], v0 offset:0x1800
	ds_read_b64_tr_b16 v[222:223], v0 offset:0x1c00
	ds_read_b64_tr_b16 v[228:229], v0 offset:0x1a00
	ds_read_b64_tr_b16 v[230:231], v0 offset:0x1e00
	v_mfma_f32_32x32x16_bf16 v[18:33], v[34:37], v[78:81], v[18:33]
	v_add_f32_e32 v238, v82, v195
	v_add_f32_e32 v239, v84, v196
	v_add_f32_e32 v240, v83, v85
	v_add_f32_e32 v241, v86, v87
	v_add_f32_e32 v238, v238, v239
	v_add_f32_e32 v240, v240, v241
	v_mfma_f32_32x32x16_bf16 v[2:17], v[34:37], v[74:77], v[2:17]
	v_max_f32_e32 v34, v114, v115
	v_max3_f32 v35, v116, v117, v99
	v_max3_f32 v34, v34, v98, v100
	v_max3_f32 v35, v35, v118, v119
	v_mfma_f32_32x32x16_bf16 v[18:33], v[42:45], v[70:73], v[18:33]
	v_max3_f32 v34, v34, v101, v120
	v_max3_f32 v35, v35, v102, v103
	v_add_f32_e32 v238, v240, v238
	v_add_f32_e32 v239, v88, v89
	v_add_f32_e32 v241, v90, v91
	v_mfma_f32_32x32x16_bf16 v[2:17], v[42:45], v[66:69], v[2:17]
	v_max3_f32 v34, v34, v121, v104
	v_max3_f32 v34, v34, v105, v124
	v_max3_f32 v35, v35, v122, v123
	v_add_f32_e32 v239, v239, v241
	v_add_f32_e32 v240, v92, v93
	v_add_f32_e32 v241, v94, v95
	s_waitcnt lgkmcnt(0)
	v_mfma_f32_32x32x16_bf16 v[18:33], v[46:49], v[212:215], v[18:33]
	v_max3_f32 v34, v34, v125, v108
	v_max3_f32 v35, v35, v106, v107
	v_add_f32_e32 v238, v239, v238
	v_add_f32_e32 v240, v240, v241
	s_waitcnt vmcnt(3)
	v_add_u32_e32 v67, s69, v187
	ds_write_b128 v67, v[162:165]
	v_mfma_f32_32x32x16_bf16 v[2:17], v[46:49], v[216:219], v[2:17]
	v_max3_f32 v34, v34, v109, v128
	v_max3_f32 v35, v35, v126, v127
	v_add_f32_e32 v238, v240, v238
	v_add_f32_e32 v239, v96, v97
	v_add_f32_e32 v241, v197, v198
	s_waitcnt vmcnt(2)
	ds_write_b128 v188, v[166:169] offset:24576
	v_mfma_f32_32x32x16_bf16 v[18:33], v[38:41], v[220:223], v[18:33]
	v_max3_f32 v34, v34, v129, v112
	v_max3_f32 v35, v35, v110, v111
	v_add_f32_e32 v239, v239, v241
	v_add_f32_e32 v240, v199, v200
	v_add_f32_e32 v241, v201, v202
	v_add_f32_e32 v238, v239, v238
	v_add_f32_e32 v240, v240, v241
	v_mfma_f32_32x32x16_bf16 v[2:17], v[38:41], v[228:231], v[2:17]
	v_max3_f32 v34, v34, v113, v35
	v_cmp_lt_f32_e32 vcc, s35, v34
	v_add_f32_e32 v238, v240, v238
	v_add_f32_e32 v239, v203, v204
	v_add_f32_e32 v241, v205, v206
	v_add_f32_e32 v239, v239, v241
	v_add_f32_e32 v240, v207, v208
	v_add_f32_e32 v241, v209, v210
	v_add_f32_e32 v238, v239, v238
	v_add_f32_e32 v240, v240, v241
	v_add_f32_e32 v238, v240, v238
	v_add_f32_e32 v194, v194, v238
	s_cbranch_vccnz .Lmy_y272
